# v28: v27 + P2 pooling-state copy loop: iterations 2-4 issued together (three loads in flight, d16_hi load for the bf16 source)
# baseline (speedup 1.0000x reference)
; __device__ __forceinline__ float bf2f(unsigned b) { return __uint_as_float(b << 16); }
; __global__ void __launch_bounds__(512, 2) mega_fwd(Args args) {
;     ...
;         for (int idx = gt; idx < 15 * 1024 + 32 * 15 * 1024; idx += NGT) {
;             if (idx < 15 * 1024) { const int e = idx >> 10, c = idx & 1023; out[O_PSP + idx] = bf2f(PROJ[(size_t)(T - 15 + e) * INW + c]); }
;             else { const int j = idx - 15 * 1024, b = j / (15 * 1024), e = (j >> 10) % 15, c = j & 1023;
;                 out[O_SSP + j] = (e + 4 < 15) ? state_pool[((size_t)b * 15 + e + 4) * 1024 + c] : bf2f(PROJ[(size_t)(T + b * 4 + e + 4 - 15) * INW + c]); }
;         }
.LBB0_324:
	s_or_b64 exec, exec, s[20:21]
	s_mov_b64 s[18:19], exec
	s_load_dwordx2 s[30:31], s[8:9], 0xf8
	s_load_dwordx2 s[44:45], s[8:9], 0xf0
	s_load_dwordx2 s[46:47], s[8:9], 0x10
	v_add_u32_e32 v208, s40, v2
	v_add_u32_e32 v216, s40, v208
	v_add_u32_e32 v224, s40, v216
	s_waitcnt lgkmcnt(0)
	v_mov_b32_e32 v214, 0
	v_and_b32_e32 v209, 0x3ff, v208
	v_add_u32_e32 v210, 0xffffc400, v208
	v_mul_hi_u32 v211, v210, s15
	v_lshrrev_b32_e32 v210, 10, v210
	v_lshrrev_b32_e32 v215, 13, v211
	v_mul_u32_u24_e32 v211, 0x8889, v210
	v_lshrrev_b32_e32 v211, 19, v211
	v_mul_lo_u16_e32 v211, 15, v211
	v_sub_u16_e32 v211, v210, v211
	v_cmp_lt_u16_e32 vcc, 10, v211
	s_and_saveexec_b64 s[22:23], vcc
	s_xor_b64 s[22:23], exec, s[22:23]
	v_lshlrev_b32_e32 v210, 2, v215
	v_add3_u32 v212, v210, v211, s27
	v_mov_b32_e32 v213, 0
	v_lshlrev_b64 v[212:213], 13, v[212:213]
	v_lshl_add_u64 v[212:213], s[30:31], 0, v[212:213]
	v_lshlrev_b32_e32 v210, 1, v209
	v_add_co_u32_e32 v212, vcc, v210, v212
	s_nop 1
	v_addc_co_u32_e32 v213, vcc, 0, v213, vcc
	v_add_co_u32_e32 v212, vcc, 0x15d00000, v212
	s_nop 1
	v_addc_co_u32_e32 v213, vcc, 0, v213, vcc
	global_load_short_d16_hi v214, v[212:213], off
	s_nop 1
	s_mov_b64 exec, s[22:23]
	v_mul_u32_u24_e32 v210, 15, v215
	v_add3_u32 v212, v210, v211, 4
	v_mov_b32_e32 v213, 0
	v_lshlrev_b64 v[212:213], 12, v[212:213]
	v_lshl_add_u64 v[212:213], s[46:47], 0, v[212:213]
	v_lshlrev_b32_e32 v210, 2, v209
	v_add_co_u32_e32 v212, vcc, v210, v212
	s_nop 1
	v_addc_co_u32_e32 v213, vcc, 0, v213, vcc
	global_load_dword v214, v[212:213], off
	s_nop 1
	s_mov_b64 exec, s[18:19]
	v_mov_b32_e32 v209, 0
	v_lshl_add_u64 v[212:213], v[208:209], 2, s[44:45]
	v_add_co_u32_e32 v212, vcc, 0x920b000, v212
	s_nop 1
	v_addc_co_u32_e32 v213, vcc, 0, v213, vcc
	v_mov_b32_e32 v222, 0
	v_and_b32_e32 v217, 0x3ff, v216
	v_add_u32_e32 v218, 0xffffc400, v216
	v_mul_hi_u32 v219, v218, s15
	v_lshrrev_b32_e32 v218, 10, v218
	v_lshrrev_b32_e32 v223, 13, v219
	v_mul_u32_u24_e32 v219, 0x8889, v218
	v_lshrrev_b32_e32 v219, 19, v219
	v_mul_lo_u16_e32 v219, 15, v219
	v_sub_u16_e32 v219, v218, v219
	v_cmp_lt_u16_e32 vcc, 10, v219
	s_and_saveexec_b64 s[22:23], vcc
	s_xor_b64 s[22:23], exec, s[22:23]
	v_lshlrev_b32_e32 v218, 2, v223
	v_add3_u32 v220, v218, v219, s27
	v_mov_b32_e32 v221, 0
	v_lshlrev_b64 v[220:221], 13, v[220:221]
	v_lshl_add_u64 v[220:221], s[30:31], 0, v[220:221]
	v_lshlrev_b32_e32 v218, 1, v217
	v_add_co_u32_e32 v220, vcc, v218, v220
	s_nop 1
	v_addc_co_u32_e32 v221, vcc, 0, v221, vcc
	v_add_co_u32_e32 v220, vcc, 0x15d00000, v220
	s_nop 1
	v_addc_co_u32_e32 v221, vcc, 0, v221, vcc
	global_load_short_d16_hi v222, v[220:221], off
	s_nop 1
	s_mov_b64 exec, s[22:23]
	v_mul_u32_u24_e32 v218, 15, v223
	v_add3_u32 v220, v218, v219, 4
	v_mov_b32_e32 v221, 0
	v_lshlrev_b64 v[220:221], 12, v[220:221]
	v_lshl_add_u64 v[220:221], s[46:47], 0, v[220:221]
	v_lshlrev_b32_e32 v218, 2, v217
	v_add_co_u32_e32 v220, vcc, v218, v220
	s_nop 1
	v_addc_co_u32_e32 v221, vcc, 0, v221, vcc
	global_load_dword v222, v[220:221], off
	s_nop 1
	s_mov_b64 exec, s[18:19]
	v_mov_b32_e32 v217, 0
	v_lshl_add_u64 v[220:221], v[216:217], 2, s[44:45]
	v_add_co_u32_e32 v220, vcc, 0x920b000, v220
	s_nop 1
	v_addc_co_u32_e32 v221, vcc, 0, v221, vcc
	v_cmp_ge_i32_e32 vcc, s28, v224
	s_and_saveexec_b64 s[20:21], vcc
	v_mov_b32_e32 v230, 0
	v_and_b32_e32 v225, 0x3ff, v224
	v_add_u32_e32 v226, 0xffffc400, v224
	v_mul_hi_u32 v227, v226, s15
	v_lshrrev_b32_e32 v226, 10, v226
	v_lshrrev_b32_e32 v231, 13, v227
	v_mul_u32_u24_e32 v227, 0x8889, v226
	v_lshrrev_b32_e32 v227, 19, v227
	v_mul_lo_u16_e32 v227, 15, v227
	v_sub_u16_e32 v227, v226, v227
	v_cmp_lt_u16_e32 vcc, 10, v227
	s_and_saveexec_b64 s[22:23], vcc
	s_xor_b64 s[22:23], exec, s[22:23]
	v_lshlrev_b32_e32 v226, 2, v231
	v_add3_u32 v228, v226, v227, s27
	v_mov_b32_e32 v229, 0
	v_lshlrev_b64 v[228:229], 13, v[228:229]
	v_lshl_add_u64 v[228:229], s[30:31], 0, v[228:229]
	v_lshlrev_b32_e32 v226, 1, v225
	v_add_co_u32_e32 v228, vcc, v226, v228
	s_nop 1
	v_addc_co_u32_e32 v229, vcc, 0, v229, vcc
	v_add_co_u32_e32 v228, vcc, 0x15d00000, v228
	s_nop 1
	v_addc_co_u32_e32 v229, vcc, 0, v229, vcc
	global_load_short_d16_hi v230, v[228:229], off
	s_nop 1
	s_mov_b64 exec, s[22:23]
	v_mul_u32_u24_e32 v226, 15, v231
	v_add3_u32 v228, v226, v227, 4
	v_mov_b32_e32 v229, 0
	v_lshlrev_b64 v[228:229], 12, v[228:229]
	v_lshl_add_u64 v[228:229], s[46:47], 0, v[228:229]
	v_lshlrev_b32_e32 v226, 2, v225
	v_add_co_u32_e32 v228, vcc, v226, v228
	s_nop 1
	v_addc_co_u32_e32 v229, vcc, 0, v229, vcc
	global_load_dword v230, v[228:229], off
	s_nop 1
	s_mov_b64 exec, s[20:21]
	v_mov_b32_e32 v225, 0
	v_lshl_add_u64 v[228:229], v[224:225], 2, s[44:45]
	v_add_co_u32_e32 v228, vcc, 0x920b000, v228
	s_nop 1
	v_addc_co_u32_e32 v229, vcc, 0, v229, vcc
	s_mov_b64 exec, s[18:19]
	s_waitcnt vmcnt(0)
	global_store_dword v[212:213], v214, off
	global_store_dword v[220:221], v222, off
	v_cmp_ge_i32_e32 vcc, s28, v224
	s_and_saveexec_b64 s[20:21], vcc
	global_store_dword v[228:229], v230, off
	s_mov_b64 exec, s[18:19]
	s_branch .LBB0_333
